# half 1 paces its up-front weight conversion (one s_sleep per item) so it disturbs half 0's layer 0 less; it had slack before the global barrier
# baseline (speedup 1.0000x reference)
.LBB0_125:
	s_sleep 100
	s_addk_i32 s26, 0x400
	s_cmpk_lt_i32 s60, 0x2d00
	s_cbranch_scc0 .LBB0_148
